# code placement (9.3): the 8 GEMM K-loop heads pinned to 64-byte boundaries with s_nop fill, on top of v075
# baseline (speedup 1.0000x reference)
; #define PG8_LAS __attribute__((address_space(3)))
; template <class Epi, class Sched, bool ALIGN_EPI = false, bool SP2 = false>
; __device__ __forceinline__ void gemm_phase(PG8_LAS unsigned char* lds, const Gemm g, const Sched& S, const Epi& E, int tid_in) {
;     ...
;         if constexpr (rowsc_of<Epi>::v) __builtin_amdgcn_global_load_lds((const unsigned*)(E.SSQ + cur.pm * BM + lane * 4), (PG8_LAS unsigned*)(lds + RS_LDS_OFF + wid * 1024), 16, 0, 0);
;         for (int t = 0; t < nt; t += 2) {
;             const bool last = (t == nt - 2);
;             const char* a1 = cA + (size_t)(t + 1) * kstep;
;             const char* a2 = last ? nA : cA + (size_t)(t + 2) * kstep; const char* b2 = last ? nB : cB + (size_t)(t + 2) * kstep;
;             const char* a3 = a2 + kstep; const char* b3 = b2 + kstep;
;     ...
;         for (int a = 0; a < 2; ++a)
; #pragma unroll
;             for (int b = 0; b < 2; ++b)
; #pragma unroll
;                 for (int m = 0; m < 4; ++m)
; #pragma unroll
;                     for (int n = 0; n < 2; ++n) acc[a][b][m][n] = (f32x4){0.f, 0.f, 0.f, 0.f};
;         }
.LBB0_281:
	s_lshl_b32 s22, s28, 8
	s_ashr_i32 s23, s22, 31
	s_mov_b32 m0, s41
	v_lshl_add_u64 v[2:3], s[22:23], 2, v[136:137]
	global_load_lds_dwordx4 v[2:3], off
	s_add_u32 s24, s24, 0x80080
	s_addc_u32 s25, s25, 0
	s_add_u32 s15, s26, 0x100
	v_mov_b32_e32 v2, 0
	s_addc_u32 s17, s27, 0
	s_mov_b32 s23, -2
	v_mov_b32_e32 v3, v2
	v_mov_b32_e32 v4, v2
	v_mov_b32_e32 v5, v2
	v_mov_b32_e32 v10, v2
	v_mov_b32_e32 v11, v2
	v_mov_b32_e32 v12, v2
	v_mov_b32_e32 v13, v2
	v_mov_b32_e32 v18, v2
	v_mov_b32_e32 v19, v2
	v_mov_b32_e32 v20, v2
	v_mov_b32_e32 v21, v2
	v_mov_b32_e32 v26, v2
	v_mov_b32_e32 v27, v2
	v_mov_b32_e32 v28, v2
	v_mov_b32_e32 v29, v2
	v_mov_b32_e32 v34, v2
	v_mov_b32_e32 v35, v2
	v_mov_b32_e32 v36, v2
	v_mov_b32_e32 v37, v2
	v_mov_b32_e32 v42, v2
	v_mov_b32_e32 v43, v2
	v_mov_b32_e32 v44, v2
	v_mov_b32_e32 v45, v2
	v_mov_b32_e32 v50, v2
	v_mov_b32_e32 v51, v2
	v_mov_b32_e32 v52, v2
	v_mov_b32_e32 v53, v2
	v_mov_b32_e32 v58, v2
	v_mov_b32_e32 v59, v2
	v_mov_b32_e32 v60, v2
	v_mov_b32_e32 v61, v2
	v_mov_b32_e32 v6, v2
	v_mov_b32_e32 v7, v2
	v_mov_b32_e32 v8, v2
	v_mov_b32_e32 v9, v2
	v_mov_b32_e32 v14, v2
	v_mov_b32_e32 v15, v2
	v_mov_b32_e32 v16, v2
	v_mov_b32_e32 v17, v2
	v_mov_b32_e32 v22, v2
	v_mov_b32_e32 v23, v2
	v_mov_b32_e32 v24, v2
	v_mov_b32_e32 v25, v2
	v_mov_b32_e32 v30, v2
	v_mov_b32_e32 v31, v2
	v_mov_b32_e32 v32, v2
	v_mov_b32_e32 v33, v2
	v_mov_b32_e32 v38, v2
	v_mov_b32_e32 v39, v2
	v_mov_b32_e32 v40, v2
	v_mov_b32_e32 v41, v2
	v_mov_b32_e32 v46, v2
	v_mov_b32_e32 v47, v2
	v_mov_b32_e32 v48, v2
	v_mov_b32_e32 v49, v2
	v_mov_b32_e32 v54, v2
	v_mov_b32_e32 v55, v2
	v_mov_b32_e32 v56, v2
	v_mov_b32_e32 v57, v2
	v_mov_b32_e32 v62, v2
	v_mov_b32_e32 v63, v2
	v_mov_b32_e32 v64, v2
	v_mov_b32_e32 v65, v2
	v_mov_b32_e32 v66, v2
	v_mov_b32_e32 v67, v2
	v_mov_b32_e32 v68, v2
	v_mov_b32_e32 v69, v2
	v_mov_b32_e32 v74, v2
	v_mov_b32_e32 v75, v2
	v_mov_b32_e32 v76, v2
	v_mov_b32_e32 v77, v2
	v_mov_b32_e32 v82, v2
	v_mov_b32_e32 v83, v2
	v_mov_b32_e32 v84, v2
	v_mov_b32_e32 v85, v2
	v_mov_b32_e32 v90, v2
	v_mov_b32_e32 v91, v2
	v_mov_b32_e32 v92, v2
	v_mov_b32_e32 v93, v2
	v_mov_b32_e32 v98, v2
	v_mov_b32_e32 v99, v2
	v_mov_b32_e32 v100, v2
	v_mov_b32_e32 v101, v2
	v_mov_b32_e32 v106, v2
	v_mov_b32_e32 v107, v2
	v_mov_b32_e32 v108, v2
	v_mov_b32_e32 v109, v2
	v_mov_b32_e32 v114, v2
	v_mov_b32_e32 v115, v2
	v_mov_b32_e32 v116, v2
	v_mov_b32_e32 v117, v2
	v_mov_b32_e32 v122, v2
	v_mov_b32_e32 v123, v2
	v_mov_b32_e32 v124, v2
	v_mov_b32_e32 v125, v2
	v_mov_b32_e32 v70, v2
	v_mov_b32_e32 v71, v2
	v_mov_b32_e32 v72, v2
	v_mov_b32_e32 v73, v2
	v_mov_b32_e32 v78, v2
	v_mov_b32_e32 v79, v2
	v_mov_b32_e32 v80, v2
	v_mov_b32_e32 v81, v2
	v_mov_b32_e32 v86, v2
	v_mov_b32_e32 v87, v2
	v_mov_b32_e32 v88, v2
	v_mov_b32_e32 v89, v2
	v_mov_b32_e32 v94, v2
	v_mov_b32_e32 v95, v2
	v_mov_b32_e32 v96, v2
	v_mov_b32_e32 v97, v2
	v_mov_b32_e32 v102, v2
	v_mov_b32_e32 v103, v2
	v_mov_b32_e32 v104, v2
	v_mov_b32_e32 v105, v2
	v_mov_b32_e32 v110, v2
	v_mov_b32_e32 v111, v2
	v_mov_b32_e32 v112, v2
	v_mov_b32_e32 v113, v2
	v_mov_b32_e32 v118, v2
	v_mov_b32_e32 v119, v2
	v_mov_b32_e32 v120, v2
	v_mov_b32_e32 v121, v2
	v_mov_b32_e32 v126, v2
	v_mov_b32_e32 v127, v2
	v_mov_b32_e32 v128, v2
	v_mov_b32_e32 v129, v2
	.p2alignl 6, 3212836864

; #define PG8_LAS __attribute__((address_space(3)))
;     __device__ __forceinline__ bool next(int i, Unit& u) const { if (!StaticOrder::next(i, u)) return false; u.pm = 0; u.pn = 0; u.a = A; u.b = Bt; return true; }
; template <class Epi, class Sched, bool ALIGN_EPI = false, bool SP2 = false>
; __device__ __forceinline__ void gemm_phase(PG8_LAS unsigned char* lds, const Gemm g, const Sched& S, const Epi& E, int tid_in) {
;     ...
;         const bool has_next = S.next(ui + 1, nxt);
;         const char* nA = has_next ? nxt.a : cA; const char* nB = has_next ? nxt.b : cB;
;         const int nt = cur.nk;
;         if constexpr (rowsc_of<Epi>::v) __builtin_amdgcn_global_load_lds((const unsigned*)(E.SSQ + cur.pm * BM + lane * 4), (PG8_LAS unsigned*)(lds + RS_LDS_OFF + wid * 1024), 16, 0, 0);
;         for (int t = 0; t < nt; t += 2) {
;             const bool last = (t == nt - 2);
;             const char* a1 = cA + (size_t)(t + 1) * kstep;
;             const char* a2 = last ? nA : cA + (size_t)(t + 2) * kstep; const char* b2 = last ? nB : cB + (size_t)(t + 2) * kstep;
;             const char* a3 = a2 + kstep; const char* b3 = b2 + kstep;
.LBB0_351:
	s_and_b64 s[4:5], s[24:25], exec
	s_cselect_b32 s46, s21, s9
	s_cselect_b32 s47, s20, s8
	s_cselect_b32 s67, s23, s27
	s_cselect_b32 s68, s22, s26
	s_add_i32 s70, s66, -2
	s_add_u32 s76, s26, 0x100
	s_addc_u32 s79, s27, 0
	s_mov_b32 s28, 0
	.p2alignl 6, 3212836864

; #define PG8_LAS __attribute__((address_space(3)))
; template <class Epi, class Sched, bool ALIGN_EPI = false, bool SP2 = false>
; __device__ __forceinline__ void gemm_phase(PG8_LAS unsigned char* lds, const Gemm g, const Sched& S, const Epi& E, int tid_in) {
;     ...
;         if constexpr (rowsc_of<Epi>::v) __builtin_amdgcn_global_load_lds((const unsigned*)(E.SSQ + cur.pm * BM + lane * 4), (PG8_LAS unsigned*)(lds + RS_LDS_OFF + wid * 1024), 16, 0, 0);
;         for (int t = 0; t < nt; t += 2) {
;             const bool last = (t == nt - 2);
;             const char* a1 = cA + (size_t)(t + 1) * kstep;
;             const char* a2 = last ? nA : cA + (size_t)(t + 2) * kstep; const char* b2 = last ? nB : cB + (size_t)(t + 2) * kstep;
;             const char* a3 = a2 + kstep; const char* b3 = b2 + kstep;
;     ...
;         for (int a = 0; a < 2; ++a)
; #pragma unroll
;             for (int b = 0; b < 2; ++b)
; #pragma unroll
;                 for (int m = 0; m < 4; ++m)
; #pragma unroll
;                     for (int n = 0; n < 2; ++n) acc[a][b][m][n] = (f32x4){0.f, 0.f, 0.f, 0.f};
;         }
.LBB0_512:
	s_lshl_b32 s12, s30, 8
	s_ashr_i32 s13, s12, 31
	s_mov_b32 m0, s49
	v_lshl_add_u64 v[2:3], s[12:13], 2, v[136:137]
	global_load_lds_dwordx4 v[2:3], off
	s_add_u32 s14, s14, 0x80080
	s_addc_u32 s15, s15, 0
	s_add_u32 s13, s28, 0x100
	v_mov_b32_e32 v2, 0
	s_addc_u32 s21, s29, 0
	s_mov_b32 s23, -2
	v_mov_b32_e32 v3, v2
	v_mov_b32_e32 v4, v2
	v_mov_b32_e32 v5, v2
	v_mov_b32_e32 v6, v2
	v_mov_b32_e32 v7, v2
	v_mov_b32_e32 v8, v2
	v_mov_b32_e32 v9, v2
	v_mov_b32_e32 v18, v2
	v_mov_b32_e32 v19, v2
	v_mov_b32_e32 v20, v2
	v_mov_b32_e32 v21, v2
	v_mov_b32_e32 v22, v2
	v_mov_b32_e32 v23, v2
	v_mov_b32_e32 v24, v2
	v_mov_b32_e32 v25, v2
	v_mov_b32_e32 v34, v2
	v_mov_b32_e32 v35, v2
	v_mov_b32_e32 v36, v2
	v_mov_b32_e32 v37, v2
	v_mov_b32_e32 v38, v2
	v_mov_b32_e32 v39, v2
	v_mov_b32_e32 v40, v2
	v_mov_b32_e32 v41, v2
	v_mov_b32_e32 v50, v2
	v_mov_b32_e32 v51, v2
	v_mov_b32_e32 v52, v2
	v_mov_b32_e32 v53, v2
	v_mov_b32_e32 v54, v2
	v_mov_b32_e32 v55, v2
	v_mov_b32_e32 v56, v2
	v_mov_b32_e32 v57, v2
	v_mov_b32_e32 v10, v2
	v_mov_b32_e32 v11, v2
	v_mov_b32_e32 v12, v2
	v_mov_b32_e32 v13, v2
	v_mov_b32_e32 v14, v2
	v_mov_b32_e32 v15, v2
	v_mov_b32_e32 v16, v2
	v_mov_b32_e32 v17, v2
	v_mov_b32_e32 v26, v2
	v_mov_b32_e32 v27, v2
	v_mov_b32_e32 v28, v2
	v_mov_b32_e32 v29, v2
	v_mov_b32_e32 v30, v2
	v_mov_b32_e32 v31, v2
	v_mov_b32_e32 v32, v2
	v_mov_b32_e32 v33, v2
	v_mov_b32_e32 v42, v2
	v_mov_b32_e32 v43, v2
	v_mov_b32_e32 v44, v2
	v_mov_b32_e32 v45, v2
	v_mov_b32_e32 v46, v2
	v_mov_b32_e32 v47, v2
	v_mov_b32_e32 v48, v2
	v_mov_b32_e32 v49, v2
	v_mov_b32_e32 v58, v2
	v_mov_b32_e32 v59, v2
	v_mov_b32_e32 v60, v2
	v_mov_b32_e32 v61, v2
	v_mov_b32_e32 v62, v2
	v_mov_b32_e32 v63, v2
	v_mov_b32_e32 v64, v2
	v_mov_b32_e32 v65, v2
	v_mov_b32_e32 v66, v2
	v_mov_b32_e32 v67, v2
	v_mov_b32_e32 v68, v2
	v_mov_b32_e32 v69, v2
	v_mov_b32_e32 v70, v2
	v_mov_b32_e32 v71, v2
	v_mov_b32_e32 v72, v2
	v_mov_b32_e32 v73, v2
	v_mov_b32_e32 v82, v2
	v_mov_b32_e32 v83, v2
	v_mov_b32_e32 v84, v2
	v_mov_b32_e32 v85, v2
	v_mov_b32_e32 v86, v2
	v_mov_b32_e32 v87, v2
	v_mov_b32_e32 v88, v2
	v_mov_b32_e32 v89, v2
	v_mov_b32_e32 v98, v2
	v_mov_b32_e32 v99, v2
	v_mov_b32_e32 v100, v2
	v_mov_b32_e32 v101, v2
	v_mov_b32_e32 v102, v2
	v_mov_b32_e32 v103, v2
	v_mov_b32_e32 v104, v2
	v_mov_b32_e32 v105, v2
	v_mov_b32_e32 v114, v2
	v_mov_b32_e32 v115, v2
	v_mov_b32_e32 v116, v2
	v_mov_b32_e32 v117, v2
	v_mov_b32_e32 v118, v2
	v_mov_b32_e32 v119, v2
	v_mov_b32_e32 v120, v2
	v_mov_b32_e32 v121, v2
	v_mov_b32_e32 v74, v2
	v_mov_b32_e32 v75, v2
	v_mov_b32_e32 v76, v2
	v_mov_b32_e32 v77, v2
	v_mov_b32_e32 v78, v2
	v_mov_b32_e32 v79, v2
	v_mov_b32_e32 v80, v2
	v_mov_b32_e32 v81, v2
	v_mov_b32_e32 v90, v2
	v_mov_b32_e32 v91, v2
	v_mov_b32_e32 v92, v2
	v_mov_b32_e32 v93, v2
	v_mov_b32_e32 v94, v2
	v_mov_b32_e32 v95, v2
	v_mov_b32_e32 v96, v2
	v_mov_b32_e32 v97, v2
	v_mov_b32_e32 v106, v2
	v_mov_b32_e32 v107, v2
	v_mov_b32_e32 v108, v2
	v_mov_b32_e32 v109, v2
	v_mov_b32_e32 v110, v2
	v_mov_b32_e32 v111, v2
	v_mov_b32_e32 v112, v2
	v_mov_b32_e32 v113, v2
	v_mov_b32_e32 v122, v2
	v_mov_b32_e32 v123, v2
	v_mov_b32_e32 v124, v2
	v_mov_b32_e32 v125, v2
	v_mov_b32_e32 v126, v2
	v_mov_b32_e32 v127, v2
	v_mov_b32_e32 v128, v2
	v_mov_b32_e32 v129, v2
	.p2alignl 6, 3212836864

; template <class Epi, class Sched, bool ALIGN_EPI = false, bool SP2 = false>
; __device__ __forceinline__ void gemm_phase(PG8_LAS unsigned char* lds, const Gemm g, const Sched& S, const Epi& E, int tid_in) {
;     ...
;             const char* a1 = cA + (size_t)(t + 1) * kstep;
;             const char* a2 = last ? nA : cA + (size_t)(t + 2) * kstep; const char* b2 = last ? nB : cB + (size_t)(t + 2) * kstep;
;             const char* a3 = a2 + kstep; const char* b3 = b2 + kstep;
;     ...
;         for (int a = 0; a < 2; ++a)
; #pragma unroll
;             for (int b = 0; b < 2; ++b)
; #pragma unroll
;                 for (int m = 0; m < 4; ++m)
; #pragma unroll
;                     for (int n = 0; n < 2; ++n) acc[a][b][m][n] = (f32x4){0.f, 0.f, 0.f, 0.f};
;         }
.LBB0_626:
	s_add_u32 s0, s22, 0x100
	v_mov_b32_e32 v2, 0
	s_addc_u32 s15, s23, 0
	s_mov_b32 s48, -2
	v_mov_b32_e32 v3, v2
	v_mov_b32_e32 v4, v2
	v_mov_b32_e32 v5, v2
	v_mov_b32_e32 v6, v2
	v_mov_b32_e32 v7, v2
	v_mov_b32_e32 v8, v2
	v_mov_b32_e32 v9, v2
	v_mov_b32_e32 v14, v2
	v_mov_b32_e32 v15, v2
	v_mov_b32_e32 v16, v2
	v_mov_b32_e32 v17, v2
	v_mov_b32_e32 v22, v2
	v_mov_b32_e32 v23, v2
	v_mov_b32_e32 v24, v2
	v_mov_b32_e32 v25, v2
	v_mov_b32_e32 v30, v2
	v_mov_b32_e32 v31, v2
	v_mov_b32_e32 v32, v2
	v_mov_b32_e32 v33, v2
	v_mov_b32_e32 v38, v2
	v_mov_b32_e32 v39, v2
	v_mov_b32_e32 v40, v2
	v_mov_b32_e32 v41, v2
	v_mov_b32_e32 v46, v2
	v_mov_b32_e32 v47, v2
	v_mov_b32_e32 v48, v2
	v_mov_b32_e32 v49, v2
	v_mov_b32_e32 v54, v2
	v_mov_b32_e32 v55, v2
	v_mov_b32_e32 v56, v2
	v_mov_b32_e32 v57, v2
	v_mov_b32_e32 v10, v2
	v_mov_b32_e32 v11, v2
	v_mov_b32_e32 v12, v2
	v_mov_b32_e32 v13, v2
	v_mov_b32_e32 v18, v2
	v_mov_b32_e32 v19, v2
	v_mov_b32_e32 v20, v2
	v_mov_b32_e32 v21, v2
	v_mov_b32_e32 v26, v2
	v_mov_b32_e32 v27, v2
	v_mov_b32_e32 v28, v2
	v_mov_b32_e32 v29, v2
	v_mov_b32_e32 v34, v2
	v_mov_b32_e32 v35, v2
	v_mov_b32_e32 v36, v2
	v_mov_b32_e32 v37, v2
	v_mov_b32_e32 v42, v2
	v_mov_b32_e32 v43, v2
	v_mov_b32_e32 v44, v2
	v_mov_b32_e32 v45, v2
	v_mov_b32_e32 v50, v2
	v_mov_b32_e32 v51, v2
	v_mov_b32_e32 v52, v2
	v_mov_b32_e32 v53, v2
	v_mov_b32_e32 v58, v2
	v_mov_b32_e32 v59, v2
	v_mov_b32_e32 v60, v2
	v_mov_b32_e32 v61, v2
	v_mov_b32_e32 v62, v2
	v_mov_b32_e32 v63, v2
	v_mov_b32_e32 v64, v2
	v_mov_b32_e32 v65, v2
	v_mov_b32_e32 v66, v2
	v_mov_b32_e32 v67, v2
	v_mov_b32_e32 v68, v2
	v_mov_b32_e32 v69, v2
	v_mov_b32_e32 v70, v2
	v_mov_b32_e32 v71, v2
	v_mov_b32_e32 v72, v2
	v_mov_b32_e32 v73, v2
	v_mov_b32_e32 v78, v2
	v_mov_b32_e32 v79, v2
	v_mov_b32_e32 v80, v2
	v_mov_b32_e32 v81, v2
	v_mov_b32_e32 v86, v2
	v_mov_b32_e32 v87, v2
	v_mov_b32_e32 v88, v2
	v_mov_b32_e32 v89, v2
	v_mov_b32_e32 v94, v2
	v_mov_b32_e32 v95, v2
	v_mov_b32_e32 v96, v2
	v_mov_b32_e32 v97, v2
	v_mov_b32_e32 v102, v2
	v_mov_b32_e32 v103, v2
	v_mov_b32_e32 v104, v2
	v_mov_b32_e32 v105, v2
	v_mov_b32_e32 v110, v2
	v_mov_b32_e32 v111, v2
	v_mov_b32_e32 v112, v2
	v_mov_b32_e32 v113, v2
	v_mov_b32_e32 v118, v2
	v_mov_b32_e32 v119, v2
	v_mov_b32_e32 v120, v2
	v_mov_b32_e32 v121, v2
	v_mov_b32_e32 v74, v2
	v_mov_b32_e32 v75, v2
	v_mov_b32_e32 v76, v2
	v_mov_b32_e32 v77, v2
	v_mov_b32_e32 v82, v2
	v_mov_b32_e32 v83, v2
	v_mov_b32_e32 v84, v2
	v_mov_b32_e32 v85, v2
	v_mov_b32_e32 v90, v2
	v_mov_b32_e32 v91, v2
	v_mov_b32_e32 v92, v2
	v_mov_b32_e32 v93, v2
	v_mov_b32_e32 v98, v2
	v_mov_b32_e32 v99, v2
	v_mov_b32_e32 v100, v2
	v_mov_b32_e32 v101, v2
	v_mov_b32_e32 v106, v2
	v_mov_b32_e32 v107, v2
	v_mov_b32_e32 v108, v2
	v_mov_b32_e32 v109, v2
	v_mov_b32_e32 v114, v2
	v_mov_b32_e32 v115, v2
	v_mov_b32_e32 v116, v2
	v_mov_b32_e32 v117, v2
	v_mov_b32_e32 v122, v2
	v_mov_b32_e32 v123, v2
	v_mov_b32_e32 v124, v2
	v_mov_b32_e32 v125, v2
	v_mov_b32_e32 v126, v2
	v_mov_b32_e32 v127, v2
	v_mov_b32_e32 v128, v2
	v_mov_b32_e32 v129, v2
	.p2alignl 6, 3212836864

; #define PG8_LAS __attribute__((address_space(3)))
;     __device__ __forceinline__ bool next(int i, Unit& u) const { if (!StaticOrder::next(i, u)) return false; u.pm = 0; u.pn = 0; u.a = A; u.b = Bt; return true; }
; template <class Epi, class Sched, bool ALIGN_EPI = false, bool SP2 = false>
; __device__ __forceinline__ void gemm_phase(PG8_LAS unsigned char* lds, const Gemm g, const Sched& S, const Epi& E, int tid_in) {
;     ...
;         const bool has_next = S.next(ui + 1, nxt);
;         const char* nA = has_next ? nxt.a : cA; const char* nB = has_next ? nxt.b : cB;
;         const int nt = cur.nk;
;         if constexpr (rowsc_of<Epi>::v) __builtin_amdgcn_global_load_lds((const unsigned*)(E.SSQ + cur.pm * BM + lane * 4), (PG8_LAS unsigned*)(lds + RS_LDS_OFF + wid * 1024), 16, 0, 0);
;         for (int t = 0; t < nt; t += 2) {
;             const bool last = (t == nt - 2);
;             const char* a1 = cA + (size_t)(t + 1) * kstep;
;             const char* a2 = last ? nA : cA + (size_t)(t + 2) * kstep; const char* b2 = last ? nB : cB + (size_t)(t + 2) * kstep;
;             const char* a3 = a2 + kstep; const char* b3 = b2 + kstep;
.LBB0_899:
	s_and_b64 s[12:13], s[28:29], exec
	s_cselect_b32 s30, s25, s9
	s_cselect_b32 s31, s24, s8
	s_cselect_b32 s46, s27, s11
	s_cselect_b32 s47, s26, s10
	s_add_i32 s68, s14, -2
	s_add_u32 s8, s8, 0x40080
	s_addc_u32 s9, s9, 0
	s_add_u32 s76, s10, 0x100
	s_addc_u32 vcc_lo, s11, 0
	s_mov_b32 s10, 0
	.p2alignl 6, 3212836864

; #define PG8_LAS __attribute__((address_space(3)))
;     __device__ __forceinline__ bool next(int i, Unit& u) const { if (!StaticOrder::next(i, u)) return false; u.pm = 0; u.pn = 0; u.a = A; u.b = Bt; return true; }
; template <class Epi, class Sched, bool ALIGN_EPI = false, bool SP2 = false>
; __device__ __forceinline__ void gemm_phase(PG8_LAS unsigned char* lds, const Gemm g, const Sched& S, const Epi& E, int tid_in) {
;     ...
;         const bool has_next = S.next(ui + 1, nxt);
;         const char* nA = has_next ? nxt.a : cA; const char* nB = has_next ? nxt.b : cB;
;         const int nt = cur.nk;
;         if constexpr (rowsc_of<Epi>::v) __builtin_amdgcn_global_load_lds((const unsigned*)(E.SSQ + cur.pm * BM + lane * 4), (PG8_LAS unsigned*)(lds + RS_LDS_OFF + wid * 1024), 16, 0, 0);
;         for (int t = 0; t < nt; t += 2) {
;             const bool last = (t == nt - 2);
;             const char* a1 = cA + (size_t)(t + 1) * kstep;
;             const char* a2 = last ? nA : cA + (size_t)(t + 2) * kstep; const char* b2 = last ? nB : cB + (size_t)(t + 2) * kstep;
;             const char* a3 = a2 + kstep; const char* b3 = b2 + kstep;
.LBB0_1347:
	s_and_b64 s[28:29], s[22:23], exec
	s_cselect_b32 s46, s19, s25
	s_cselect_b32 s47, s18, s24
	s_cselect_b32 s49, s21, s27
	s_cselect_b32 s66, s20, s26
	s_add_i32 s67, s45, -2
	s_add_u32 s24, s24, 0x80080
	s_addc_u32 s25, s25, 0
	s_add_u32 s68, s26, 0x100
	s_addc_u32 s70, s27, 0
	s_mov_b32 s26, 0
	.p2alignl 6, 3212836864

; #define PG8_LAS __attribute__((address_space(3)))
; template <class Epi, class Sched, bool ALIGN_EPI = false, bool SP2 = false>
; __device__ __forceinline__ void gemm_phase(PG8_LAS unsigned char* lds, const Gemm g, const Sched& S, const Epi& E, int tid_in) {
;     ...
;         if constexpr (rowsc_of<Epi>::v) __builtin_amdgcn_global_load_lds((const unsigned*)(E.SSQ + cur.pm * BM + lane * 4), (PG8_LAS unsigned*)(lds + RS_LDS_OFF + wid * 1024), 16, 0, 0);
;         for (int t = 0; t < nt; t += 2) {
;             const bool last = (t == nt - 2);
;             const char* a1 = cA + (size_t)(t + 1) * kstep;
;             const char* a2 = last ? nA : cA + (size_t)(t + 2) * kstep; const char* b2 = last ? nB : cB + (size_t)(t + 2) * kstep;
;             const char* a3 = a2 + kstep; const char* b3 = b2 + kstep;
;     ...
;         for (int a = 0; a < 2; ++a)
; #pragma unroll
;             for (int b = 0; b < 2; ++b)
; #pragma unroll
;                 for (int m = 0; m < 4; ++m)
; #pragma unroll
;                     for (int n = 0; n < 2; ++n) acc[a][b][m][n] = (f32x4){0.f, 0.f, 0.f, 0.f};
;         }
.LBB0_1506:
	s_lshl_b32 s22, s28, 8
	s_ashr_i32 s23, s22, 31
	s_mov_b32 m0, s43
	v_lshl_add_u64 v[2:3], s[22:23], 2, v[136:137]
	global_load_lds_dwordx4 v[2:3], off
	s_add_u32 s24, s24, 0x80080
	s_addc_u32 s25, s25, 0
	s_add_u32 s15, s26, 0x100
	v_mov_b32_e32 v2, 0
	s_addc_u32 s17, s27, 0
	s_mov_b32 s23, -2
	v_mov_b32_e32 v3, v2
	v_mov_b32_e32 v4, v2
	v_mov_b32_e32 v5, v2
	v_mov_b32_e32 v10, v2
	v_mov_b32_e32 v11, v2
	v_mov_b32_e32 v12, v2
	v_mov_b32_e32 v13, v2
	v_mov_b32_e32 v18, v2
	v_mov_b32_e32 v19, v2
	v_mov_b32_e32 v20, v2
	v_mov_b32_e32 v21, v2
	v_mov_b32_e32 v26, v2
	v_mov_b32_e32 v27, v2
	v_mov_b32_e32 v28, v2
	v_mov_b32_e32 v29, v2
	v_mov_b32_e32 v34, v2
	v_mov_b32_e32 v35, v2
	v_mov_b32_e32 v36, v2
	v_mov_b32_e32 v37, v2
	v_mov_b32_e32 v42, v2
	v_mov_b32_e32 v43, v2
	v_mov_b32_e32 v44, v2
	v_mov_b32_e32 v45, v2
	v_mov_b32_e32 v50, v2
	v_mov_b32_e32 v51, v2
	v_mov_b32_e32 v52, v2
	v_mov_b32_e32 v53, v2
	v_mov_b32_e32 v58, v2
	v_mov_b32_e32 v59, v2
	v_mov_b32_e32 v60, v2
	v_mov_b32_e32 v61, v2
	v_mov_b32_e32 v6, v2
	v_mov_b32_e32 v7, v2
	v_mov_b32_e32 v8, v2
	v_mov_b32_e32 v9, v2
	v_mov_b32_e32 v14, v2
	v_mov_b32_e32 v15, v2
	v_mov_b32_e32 v16, v2
	v_mov_b32_e32 v17, v2
	v_mov_b32_e32 v22, v2
	v_mov_b32_e32 v23, v2
	v_mov_b32_e32 v24, v2
	v_mov_b32_e32 v25, v2
	v_mov_b32_e32 v30, v2
	v_mov_b32_e32 v31, v2
	v_mov_b32_e32 v32, v2
	v_mov_b32_e32 v33, v2
	v_mov_b32_e32 v38, v2
	v_mov_b32_e32 v39, v2
	v_mov_b32_e32 v40, v2
	v_mov_b32_e32 v41, v2
	v_mov_b32_e32 v46, v2
	v_mov_b32_e32 v47, v2
	v_mov_b32_e32 v48, v2
	v_mov_b32_e32 v49, v2
	v_mov_b32_e32 v54, v2
	v_mov_b32_e32 v55, v2
	v_mov_b32_e32 v56, v2
	v_mov_b32_e32 v57, v2
	v_mov_b32_e32 v62, v2
	v_mov_b32_e32 v63, v2
	v_mov_b32_e32 v64, v2
	v_mov_b32_e32 v65, v2
	v_mov_b32_e32 v66, v2
	v_mov_b32_e32 v67, v2
	v_mov_b32_e32 v68, v2
	v_mov_b32_e32 v69, v2
	v_mov_b32_e32 v74, v2
	v_mov_b32_e32 v75, v2
	v_mov_b32_e32 v76, v2
	v_mov_b32_e32 v77, v2
	v_mov_b32_e32 v82, v2
	v_mov_b32_e32 v83, v2
	v_mov_b32_e32 v84, v2
	v_mov_b32_e32 v85, v2
	v_mov_b32_e32 v90, v2
	v_mov_b32_e32 v91, v2
	v_mov_b32_e32 v92, v2
	v_mov_b32_e32 v93, v2
	v_mov_b32_e32 v98, v2
	v_mov_b32_e32 v99, v2
	v_mov_b32_e32 v100, v2
	v_mov_b32_e32 v101, v2
	v_mov_b32_e32 v106, v2
	v_mov_b32_e32 v107, v2
	v_mov_b32_e32 v108, v2
	v_mov_b32_e32 v109, v2
	v_mov_b32_e32 v114, v2
	v_mov_b32_e32 v115, v2
	v_mov_b32_e32 v116, v2
	v_mov_b32_e32 v117, v2
	v_mov_b32_e32 v122, v2
	v_mov_b32_e32 v123, v2
	v_mov_b32_e32 v124, v2
	v_mov_b32_e32 v125, v2
	v_mov_b32_e32 v70, v2
	v_mov_b32_e32 v71, v2
	v_mov_b32_e32 v72, v2
	v_mov_b32_e32 v73, v2
	v_mov_b32_e32 v78, v2
	v_mov_b32_e32 v79, v2
	v_mov_b32_e32 v80, v2
	v_mov_b32_e32 v81, v2
	v_mov_b32_e32 v86, v2
	v_mov_b32_e32 v87, v2
	v_mov_b32_e32 v88, v2
	v_mov_b32_e32 v89, v2
	v_mov_b32_e32 v94, v2
	v_mov_b32_e32 v95, v2
	v_mov_b32_e32 v96, v2
	v_mov_b32_e32 v97, v2
	v_mov_b32_e32 v102, v2
	v_mov_b32_e32 v103, v2
	v_mov_b32_e32 v104, v2
	v_mov_b32_e32 v105, v2
	v_mov_b32_e32 v110, v2
	v_mov_b32_e32 v111, v2
	v_mov_b32_e32 v112, v2
	v_mov_b32_e32 v113, v2
	v_mov_b32_e32 v118, v2
	v_mov_b32_e32 v119, v2
	v_mov_b32_e32 v120, v2
	v_mov_b32_e32 v121, v2
	v_mov_b32_e32 v126, v2
	v_mov_b32_e32 v127, v2
	v_mov_b32_e32 v128, v2
	v_mov_b32_e32 v129, v2
	.p2alignl 6, 3212836864

; #define PG8_LAS __attribute__((address_space(3)))
;     __device__ __forceinline__ bool next(int i, Unit& u) const { if (!StaticOrder::next(i, u)) return false; u.pm = 0; u.pn = 0; u.a = A; u.b = Bt; return true; }
; template <class Epi, class Sched, bool ALIGN_EPI = false, bool SP2 = false>
; __device__ __forceinline__ void gemm_phase(PG8_LAS unsigned char* lds, const Gemm g, const Sched& S, const Epi& E, int tid_in) {
;     ...
;         const bool has_next = S.next(ui + 1, nxt);
;         const char* nA = has_next ? nxt.a : cA; const char* nB = has_next ? nxt.b : cB;
;         const int nt = cur.nk;
;         if constexpr (rowsc_of<Epi>::v) __builtin_amdgcn_global_load_lds((const unsigned*)(E.SSQ + cur.pm * BM + lane * 4), (PG8_LAS unsigned*)(lds + RS_LDS_OFF + wid * 1024), 16, 0, 0);
;         for (int t = 0; t < nt; t += 2) {
;             const bool last = (t == nt - 2);
;             const char* a1 = cA + (size_t)(t + 1) * kstep;
;             const char* a2 = last ? nA : cA + (size_t)(t + 2) * kstep; const char* b2 = last ? nB : cB + (size_t)(t + 2) * kstep;
;             const char* a3 = a2 + kstep; const char* b3 = b2 + kstep;
.LBB0_1576:
	s_and_b64 s[10:11], s[34:35], exec
	s_cselect_b32 s46, s27, s7
	s_cselect_b32 s47, s26, s6
	s_cselect_b32 s76, s29, s9
	s_cselect_b32 s82, s28, s8
	s_add_i32 s83, s79, -2
	s_add_u32 s84, s8, 0x100
	s_addc_u32 s85, s9, 0
	s_mov_b32 s10, 0
	.p2alignl 6, 3212836864
